# weight-conversion bias accumulation loops: all LDS operand reads of an iteration issued before a single wait
# speedup vs baseline: 1.0092x; 1.0092x over previous
.LBB0_1219:
	v_add_u32_e32 v7, s37, v5
	ds_read_b128 v[8:11], v7
	ds_read_b128 v[14:17], v7 offset:16
	ds_read2_b32 v[18:19], v0 offset1:65
	ds_read2_b32 v[20:21], v0 offset0:130 offset1:195
	v_add_u32_e32 v7, 0x400, v0
	ds_read2_b32 v[22:23], v7 offset0:4 offset1:69
	ds_read2_b32 v[24:25], v7 offset0:134 offset1:199
	v_add_u32_e32 v0, 0x820, v0
	s_add_i32 s37, s37, 32
	s_cmpk_eq_i32 s37, 0x100
	s_waitcnt lgkmcnt(0)
	v_fmac_f32_e32 v6, v8, v18
	v_fmac_f32_e32 v6, v9, v19
	v_fmac_f32_e32 v6, v10, v20
	v_fmac_f32_e32 v6, v11, v21
	v_fmac_f32_e32 v6, v14, v22
	v_fmac_f32_e32 v6, v15, v23
	v_fmac_f32_e32 v6, v16, v24
	v_fmac_f32_e32 v6, v17, v25
	s_cbranch_scc0 .LBB0_1219
	v_lshrrev_b32_e32 v0, 6, v12
	s_movk_i32 s37, 0xa00
	v_mul_lo_u32 v0, v0, s37
	v_lshl_add_u64 v[8:9], v[0:1], 2, v[2:3]
	global_atomic_add_f32 v[8:9], v6, off
	v_add_u32_e32 v0, 0x100, v12
	v_cmp_lt_u32_e32 vcc, s50, v12
	v_add_u32_e32 v5, 0x400, v5
	s_or_b64 s[0:1], vcc, s[0:1]
	v_mov_b32_e32 v12, v0
	s_andn2_b64 exec, exec, s[0:1]
	s_cbranch_execnz .LBB0_1218
	s_or_b64 exec, exec, s[0:1]

.LBB0_1229:
	v_add_u32_e32 v7, s6, v5
	ds_read_b128 v[10:13], v7
	ds_read_b128 v[14:17], v7 offset:16
	ds_read2_b32 v[18:19], v0 offset1:65
	ds_read2_b32 v[20:21], v0 offset0:130 offset1:195
	v_add_u32_e32 v7, 0x400, v0
	ds_read2_b32 v[22:23], v7 offset0:4 offset1:69
	ds_read2_b32 v[24:25], v7 offset0:134 offset1:199
	v_add_u32_e32 v0, 0x820, v0
	s_add_i32 s6, s6, 32
	s_cmpk_eq_i32 s6, 0x100
	s_waitcnt lgkmcnt(0)
	v_fmac_f32_e32 v6, v10, v18
	v_fmac_f32_e32 v6, v11, v19
	v_fmac_f32_e32 v6, v12, v20
	v_fmac_f32_e32 v6, v13, v21
	v_fmac_f32_e32 v6, v14, v22
	v_fmac_f32_e32 v6, v15, v23
	v_fmac_f32_e32 v6, v16, v24
	v_fmac_f32_e32 v6, v17, v25
	s_cbranch_scc0 .LBB0_1229
	v_lshrrev_b32_e32 v0, 6, v9
	v_mul_lo_u32 v0, v0, s46
	v_lshl_add_u64 v[10:11], v[0:1], 2, v[2:3]
	global_atomic_add_f32 v[10:11], v6, off
	v_add_u32_e32 v0, 0x100, v9
	v_cmp_lt_u32_e32 vcc, s50, v9
	v_add_u32_e32 v5, 0x400, v5
	s_or_b64 s[4:5], vcc, s[4:5]
	v_mov_b32_e32 v9, v0
	s_andn2_b64 exec, exec, s[4:5]
	s_cbranch_execnz .LBB0_1228
	s_or_b64 exec, exec, s[4:5]
